# scheduler shift fast path plus 8 bytes of cold padding so the hot loops keep the 64-byte alignment of the previous best
# baseline (speedup 1.0000x reference)
.Lts_div_general:
	s_nop 0
	s_nop 0
	s_abs_i32 s8, s7
	v_cvt_f32_u32_e32 v48, s8
	s_sub_i32 s10, 0, s8
	s_mul_i32 s1, s1, s22
	s_sub_i32 s0, s0, s1
	v_rcp_iflag_f32_e32 v48, v48
	s_abs_i32 s9, s0
	s_xor_b32 s1, s0, s7
	s_ashr_i32 s1, s1, 31
	v_mul_f32_e32 v48, 0x4f7ffffe, v48
	v_cvt_u32_f32_e32 v48, v48
	s_nop 0
	v_readfirstlane_b32 s11, v48
	s_mul_i32 s10, s10, s11
	s_mul_hi_u32 s10, s11, s10
	s_add_i32 s11, s11, s10
	s_mul_hi_u32 s10, s9, s11
	s_mul_i32 s11, s10, s8
	s_sub_i32 s9, s9, s11
	s_add_i32 s11, s10, 1
	s_sub_i32 s27, s9, s8
	s_cmp_ge_u32 s9, s8
	s_cselect_b32 s10, s11, s10
	s_cselect_b32 s9, s27, s9
	s_add_i32 s11, s10, 1
	s_cmp_ge_u32 s9, s8
	s_cselect_b32 s8, s11, s10
	s_xor_b32 s8, s8, s1
	s_sub_i32 s52, s8, s1
	s_mul_i32 s1, s52, s7
	s_sub_i32 s0, s0, s1
	s_add_i32 s54, s0, s6
	s_mov_b64 s[6:7], -1
